# dual-block attention: block B's second score half issued before fragment 3's PV MFMAs, half of its row-max hidden in that MFMA gap
# speedup vs baseline: 1.0179x; 1.0029x over previous
.Lat_backg0a:
	v_exp_f32_e32 v96, v96
	v_exp_f32_e32 v97, v97
	v_exp_f32_e32 v98, v98
	v_exp_f32_e32 v99, v99
	v_exp_f32_e32 v100, v100
	v_exp_f32_e32 v101, v101
	v_exp_f32_e32 v102, v102
	v_exp_f32_e32 v103, v103
	v_cvt_pk_bf16_f32 v162, v96, v97
	v_cvt_pk_bf16_f32 v163, v98, v99
	v_cvt_pk_bf16_f32 v164, v100, v101
	v_cvt_pk_bf16_f32 v165, v102, v103
	v_pk_add_f32 v[128:129], v[128:129], v[96:97]
	v_pk_add_f32 v[128:129], v[128:129], v[98:99]
	v_pk_add_f32 v[128:129], v[128:129], v[100:101]
	v_pk_add_f32 v[128:129], v[128:129], v[102:103]
	s_waitcnt lgkmcnt(12)
	v_mfma_f32_32x32x16_bf16 v[0:15], v[162:165], v[168:171], v[0:15]
	v_exp_f32_e32 v104, v104
	v_exp_f32_e32 v105, v105
	v_exp_f32_e32 v106, v106
	v_exp_f32_e32 v107, v107
	v_mfma_f32_32x32x16_bf16 v[16:31], v[162:165], v[172:175], v[16:31]
	v_exp_f32_e32 v108, v108
	v_exp_f32_e32 v109, v109
	v_exp_f32_e32 v110, v110
	v_exp_f32_e32 v111, v111
	v_cvt_pk_bf16_f32 v162, v104, v105
	v_cvt_pk_bf16_f32 v163, v106, v107
	v_cvt_pk_bf16_f32 v164, v108, v109
	v_cvt_pk_bf16_f32 v165, v110, v111
	v_pk_add_f32 v[128:129], v[128:129], v[104:105]
	v_pk_add_f32 v[128:129], v[128:129], v[106:107]
	v_pk_add_f32 v[128:129], v[128:129], v[108:109]
	v_pk_add_f32 v[128:129], v[128:129], v[110:111]
	s_waitcnt lgkmcnt(8)
	v_mfma_f32_32x32x16_bf16 v[0:15], v[162:165], v[176:179], v[0:15]
	v_exp_f32_e32 v112, v112
	v_exp_f32_e32 v113, v113
	v_exp_f32_e32 v114, v114
	v_exp_f32_e32 v115, v115
	v_mfma_f32_32x32x16_bf16 v[16:31], v[162:165], v[180:183], v[16:31]
	v_mfma_f32_32x32x16_bf16 v[96:111], v[48:51], v[150:153], v[64:79]
	v_exp_f32_e32 v116, v116
	v_exp_f32_e32 v117, v117
	v_exp_f32_e32 v118, v118
	v_exp_f32_e32 v119, v119
	v_mfma_f32_32x32x16_bf16 v[96:111], v[52:55], v[154:157], v[96:111]
	v_cvt_pk_bf16_f32 v162, v112, v113
	v_cvt_pk_bf16_f32 v163, v114, v115
	v_cvt_pk_bf16_f32 v164, v116, v117
	v_cvt_pk_bf16_f32 v165, v118, v119
	v_pk_add_f32 v[128:129], v[128:129], v[112:113]
	v_pk_add_f32 v[128:129], v[128:129], v[114:115]
	v_pk_add_f32 v[128:129], v[128:129], v[116:117]
	v_pk_add_f32 v[128:129], v[128:129], v[118:119]
	s_waitcnt lgkmcnt(4)
	v_mfma_f32_32x32x16_bf16 v[0:15], v[162:165], v[184:187], v[0:15]
	v_exp_f32_e32 v120, v120
	v_exp_f32_e32 v121, v121
	v_exp_f32_e32 v122, v122
	v_exp_f32_e32 v123, v123
	v_mfma_f32_32x32x16_bf16 v[16:31], v[162:165], v[188:191], v[16:31]
	v_exp_f32_e32 v124, v124
	v_exp_f32_e32 v125, v125
	v_exp_f32_e32 v126, v126
	v_exp_f32_e32 v127, v127
	v_cvt_pk_bf16_f32 v162, v120, v121
	v_cvt_pk_bf16_f32 v163, v122, v123
	v_cvt_pk_bf16_f32 v164, v124, v125
	v_cvt_pk_bf16_f32 v165, v126, v127
	v_pk_add_f32 v[128:129], v[128:129], v[120:121]
	v_pk_add_f32 v[128:129], v[128:129], v[122:123]
	v_pk_add_f32 v[128:129], v[128:129], v[124:125]
	v_pk_add_f32 v[128:129], v[128:129], v[126:127]
	v_mfma_f32_32x32x16_bf16 v[112:127], v[56:59], v[150:153], v[64:79]
	v_mfma_f32_32x32x16_bf16 v[112:127], v[60:63], v[154:157], v[112:127]
	s_waitcnt lgkmcnt(0)
	v_mfma_f32_32x32x16_bf16 v[0:15], v[162:165], v[192:195], v[0:15]
	v_max3_f32 v132, v96, v97, v98
	v_max3_f32 v133, v99, v100, v101
	v_max3_f32 v132, v132, v102, v103
	v_max3_f32 v133, v133, v104, v105
	v_max3_f32 v132, v132, v106, v107
	v_max3_f32 v133, v133, v108, v109
	v_max3_f32 v132, v132, v110, v111
	v_mfma_f32_32x32x16_bf16 v[16:31], v[162:165], v[196:199], v[16:31]
	ds_read_b128 v[48:51], v144 offset:8192
	ds_read_b128 v[52:55], v145 offset:8192
	ds_read_b128 v[56:59], v144 offset:12288
	ds_read_b128 v[60:63], v145 offset:12288
	v_max3_f32 v133, v133, v112, v113
	v_max3_f32 v132, v132, v114, v115
	v_max3_f32 v133, v133, v116, v117
	v_max3_f32 v132, v132, v118, v119
	v_max3_f32 v133, v133, v120, v121
	v_max3_f32 v132, v132, v122, v123
	v_max3_f32 v133, v133, v124, v125
	v_max3_f32 v132, v132, v126, v127
	v_max_f32_e32 v132, v132, v133
	v_mov_b32_e32 v133, v132
	s_nop 1
	v_permlane32_swap_b32_e32 v132, v133
	v_max_f32_e32 v132, v132, v133
	s_cmp_lg_u32 s95, 0
	s_cbranch_scc1 .Lat_rareg0b
	v_cmp_lt_f32_e32 vcc, s4, v132
	s_cbranch_vccnz .Lat_rareg0b

.Lat_backg1a:
	v_exp_f32_e32 v96, v96
	v_exp_f32_e32 v97, v97
	v_exp_f32_e32 v98, v98
	v_exp_f32_e32 v99, v99
	v_exp_f32_e32 v100, v100
	v_exp_f32_e32 v101, v101
	v_exp_f32_e32 v102, v102
	v_exp_f32_e32 v103, v103
	v_cvt_pk_bf16_f32 v162, v96, v97
	v_cvt_pk_bf16_f32 v163, v98, v99
	v_cvt_pk_bf16_f32 v164, v100, v101
	v_cvt_pk_bf16_f32 v165, v102, v103
	v_pk_add_f32 v[128:129], v[128:129], v[96:97]
	v_pk_add_f32 v[128:129], v[128:129], v[98:99]
	v_pk_add_f32 v[128:129], v[128:129], v[100:101]
	v_pk_add_f32 v[128:129], v[128:129], v[102:103]
	s_waitcnt lgkmcnt(12)
	v_mfma_f32_32x32x16_bf16 v[0:15], v[162:165], v[168:171], v[0:15]
	v_exp_f32_e32 v104, v104
	v_exp_f32_e32 v105, v105
	v_exp_f32_e32 v106, v106
	v_exp_f32_e32 v107, v107
	v_mfma_f32_32x32x16_bf16 v[16:31], v[162:165], v[172:175], v[16:31]
	v_exp_f32_e32 v108, v108
	v_exp_f32_e32 v109, v109
	v_exp_f32_e32 v110, v110
	v_exp_f32_e32 v111, v111
	v_cvt_pk_bf16_f32 v162, v104, v105
	v_cvt_pk_bf16_f32 v163, v106, v107
	v_cvt_pk_bf16_f32 v164, v108, v109
	v_cvt_pk_bf16_f32 v165, v110, v111
	v_pk_add_f32 v[128:129], v[128:129], v[104:105]
	v_pk_add_f32 v[128:129], v[128:129], v[106:107]
	v_pk_add_f32 v[128:129], v[128:129], v[108:109]
	v_pk_add_f32 v[128:129], v[128:129], v[110:111]
	s_waitcnt lgkmcnt(8)
	v_mfma_f32_32x32x16_bf16 v[0:15], v[162:165], v[176:179], v[0:15]
	v_exp_f32_e32 v112, v112
	v_exp_f32_e32 v113, v113
	v_exp_f32_e32 v114, v114
	v_exp_f32_e32 v115, v115
	v_mfma_f32_32x32x16_bf16 v[16:31], v[162:165], v[180:183], v[16:31]
	v_mfma_f32_32x32x16_bf16 v[96:111], v[48:51], v[150:153], v[64:79]
	v_exp_f32_e32 v116, v116
	v_exp_f32_e32 v117, v117
	v_exp_f32_e32 v118, v118
	v_exp_f32_e32 v119, v119
	v_mfma_f32_32x32x16_bf16 v[96:111], v[52:55], v[154:157], v[96:111]
	v_cvt_pk_bf16_f32 v162, v112, v113
	v_cvt_pk_bf16_f32 v163, v114, v115
	v_cvt_pk_bf16_f32 v164, v116, v117
	v_cvt_pk_bf16_f32 v165, v118, v119
	v_pk_add_f32 v[128:129], v[128:129], v[112:113]
	v_pk_add_f32 v[128:129], v[128:129], v[114:115]
	v_pk_add_f32 v[128:129], v[128:129], v[116:117]
	v_pk_add_f32 v[128:129], v[128:129], v[118:119]
	s_waitcnt lgkmcnt(4)
	v_mfma_f32_32x32x16_bf16 v[0:15], v[162:165], v[184:187], v[0:15]
	v_exp_f32_e32 v120, v120
	v_exp_f32_e32 v121, v121
	v_exp_f32_e32 v122, v122
	v_exp_f32_e32 v123, v123
	v_mfma_f32_32x32x16_bf16 v[16:31], v[162:165], v[188:191], v[16:31]
	v_exp_f32_e32 v124, v124
	v_exp_f32_e32 v125, v125
	v_exp_f32_e32 v126, v126
	v_exp_f32_e32 v127, v127
	v_cvt_pk_bf16_f32 v162, v120, v121
	v_cvt_pk_bf16_f32 v163, v122, v123
	v_cvt_pk_bf16_f32 v164, v124, v125
	v_cvt_pk_bf16_f32 v165, v126, v127
	v_pk_add_f32 v[128:129], v[128:129], v[120:121]
	v_pk_add_f32 v[128:129], v[128:129], v[122:123]
	v_pk_add_f32 v[128:129], v[128:129], v[124:125]
	v_pk_add_f32 v[128:129], v[128:129], v[126:127]
	v_mfma_f32_32x32x16_bf16 v[112:127], v[56:59], v[150:153], v[64:79]
	v_mfma_f32_32x32x16_bf16 v[112:127], v[60:63], v[154:157], v[112:127]
	s_waitcnt lgkmcnt(0)
	v_mfma_f32_32x32x16_bf16 v[0:15], v[162:165], v[192:195], v[0:15]
	v_max3_f32 v132, v96, v97, v98
	v_max3_f32 v133, v99, v100, v101
	v_max3_f32 v132, v132, v102, v103
	v_max3_f32 v133, v133, v104, v105
	v_max3_f32 v132, v132, v106, v107
	v_max3_f32 v133, v133, v108, v109
	v_max3_f32 v132, v132, v110, v111
	v_mfma_f32_32x32x16_bf16 v[16:31], v[162:165], v[196:199], v[16:31]
	s_nop 2
	v_max3_f32 v133, v133, v112, v113
	v_max3_f32 v132, v132, v114, v115
	v_max3_f32 v133, v133, v116, v117
	v_max3_f32 v132, v132, v118, v119
	v_max3_f32 v133, v133, v120, v121
	v_max3_f32 v132, v132, v122, v123
	v_max3_f32 v133, v133, v124, v125
	v_max3_f32 v132, v132, v126, v127
	v_max_f32_e32 v132, v132, v133
	v_mov_b32_e32 v133, v132
	s_nop 1
	v_permlane32_swap_b32_e32 v132, v133
	v_max_f32_e32 v132, v132, v133
	v_cmp_lt_f32_e32 vcc, s4, v132
	s_cbranch_vccnz .Lat_rareg1b

.Lat_backg2a:
	v_exp_f32_e32 v96, v96
	v_exp_f32_e32 v97, v97
	v_exp_f32_e32 v98, v98
	v_exp_f32_e32 v99, v99
	v_exp_f32_e32 v100, v100
	v_exp_f32_e32 v101, v101
	v_exp_f32_e32 v102, v102
	v_exp_f32_e32 v103, v103
	v_cvt_pk_bf16_f32 v162, v96, v97
	v_cvt_pk_bf16_f32 v163, v98, v99
	v_cvt_pk_bf16_f32 v164, v100, v101
	v_cvt_pk_bf16_f32 v165, v102, v103
	v_pk_add_f32 v[128:129], v[128:129], v[96:97]
	v_pk_add_f32 v[128:129], v[128:129], v[98:99]
	v_pk_add_f32 v[128:129], v[128:129], v[100:101]
	v_pk_add_f32 v[128:129], v[128:129], v[102:103]
	s_waitcnt lgkmcnt(12)
	v_mfma_f32_32x32x16_bf16 v[0:15], v[162:165], v[168:171], v[0:15]
	v_exp_f32_e32 v104, v104
	v_exp_f32_e32 v105, v105
	v_exp_f32_e32 v106, v106
	v_exp_f32_e32 v107, v107
	v_mfma_f32_32x32x16_bf16 v[16:31], v[162:165], v[172:175], v[16:31]
	v_exp_f32_e32 v108, v108
	v_exp_f32_e32 v109, v109
	v_exp_f32_e32 v110, v110
	v_exp_f32_e32 v111, v111
	v_cvt_pk_bf16_f32 v162, v104, v105
	v_cvt_pk_bf16_f32 v163, v106, v107
	v_cvt_pk_bf16_f32 v164, v108, v109
	v_cvt_pk_bf16_f32 v165, v110, v111
	v_pk_add_f32 v[128:129], v[128:129], v[104:105]
	v_pk_add_f32 v[128:129], v[128:129], v[106:107]
	v_pk_add_f32 v[128:129], v[128:129], v[108:109]
	v_pk_add_f32 v[128:129], v[128:129], v[110:111]
	s_waitcnt lgkmcnt(8)
	v_mfma_f32_32x32x16_bf16 v[0:15], v[162:165], v[176:179], v[0:15]
	v_exp_f32_e32 v112, v112
	v_exp_f32_e32 v113, v113
	v_exp_f32_e32 v114, v114
	v_exp_f32_e32 v115, v115
	v_mfma_f32_32x32x16_bf16 v[16:31], v[162:165], v[180:183], v[16:31]
	v_mfma_f32_32x32x16_bf16 v[96:111], v[48:51], v[150:153], v[64:79]
	v_exp_f32_e32 v116, v116
	v_exp_f32_e32 v117, v117
	v_exp_f32_e32 v118, v118
	v_exp_f32_e32 v119, v119
	v_mfma_f32_32x32x16_bf16 v[96:111], v[52:55], v[154:157], v[96:111]
	v_cvt_pk_bf16_f32 v162, v112, v113
	v_cvt_pk_bf16_f32 v163, v114, v115
	v_cvt_pk_bf16_f32 v164, v116, v117
	v_cvt_pk_bf16_f32 v165, v118, v119
	v_pk_add_f32 v[128:129], v[128:129], v[112:113]
	v_pk_add_f32 v[128:129], v[128:129], v[114:115]
	v_pk_add_f32 v[128:129], v[128:129], v[116:117]
	v_pk_add_f32 v[128:129], v[128:129], v[118:119]
	s_waitcnt lgkmcnt(4)
	v_mfma_f32_32x32x16_bf16 v[0:15], v[162:165], v[184:187], v[0:15]
	v_exp_f32_e32 v120, v120
	v_exp_f32_e32 v121, v121
	v_exp_f32_e32 v122, v122
	v_exp_f32_e32 v123, v123
	v_mfma_f32_32x32x16_bf16 v[16:31], v[162:165], v[188:191], v[16:31]
	v_exp_f32_e32 v124, v124
	v_exp_f32_e32 v125, v125
	v_exp_f32_e32 v126, v126
	v_exp_f32_e32 v127, v127
	v_cvt_pk_bf16_f32 v162, v120, v121
	v_cvt_pk_bf16_f32 v163, v122, v123
	v_cvt_pk_bf16_f32 v164, v124, v125
	v_cvt_pk_bf16_f32 v165, v126, v127
	v_pk_add_f32 v[128:129], v[128:129], v[120:121]
	v_pk_add_f32 v[128:129], v[128:129], v[122:123]
	v_pk_add_f32 v[128:129], v[128:129], v[124:125]
	v_pk_add_f32 v[128:129], v[128:129], v[126:127]
	v_mfma_f32_32x32x16_bf16 v[112:127], v[56:59], v[150:153], v[64:79]
	v_mfma_f32_32x32x16_bf16 v[112:127], v[60:63], v[154:157], v[112:127]
	s_waitcnt lgkmcnt(0)
	v_mfma_f32_32x32x16_bf16 v[0:15], v[162:165], v[192:195], v[0:15]
	v_max3_f32 v132, v96, v97, v98
	v_max3_f32 v133, v99, v100, v101
	v_max3_f32 v132, v132, v102, v103
	v_max3_f32 v133, v133, v104, v105
	v_max3_f32 v132, v132, v106, v107
	v_max3_f32 v133, v133, v108, v109
	v_max3_f32 v132, v132, v110, v111
	v_mfma_f32_32x32x16_bf16 v[16:31], v[162:165], v[196:199], v[16:31]
	ds_read_b128 v[48:51], v144 offset:24576
	ds_read_b128 v[52:55], v145 offset:24576
	ds_read_b128 v[56:59], v144 offset:28672
	ds_read_b128 v[60:63], v145 offset:28672
	v_max3_f32 v133, v133, v112, v113
	v_max3_f32 v132, v132, v114, v115
	v_max3_f32 v133, v133, v116, v117
	v_max3_f32 v132, v132, v118, v119
	v_max3_f32 v133, v133, v120, v121
	v_max3_f32 v132, v132, v122, v123
	v_max3_f32 v133, v133, v124, v125
	v_max3_f32 v132, v132, v126, v127
	v_max_f32_e32 v132, v132, v133
	v_mov_b32_e32 v133, v132
	s_nop 1
	v_permlane32_swap_b32_e32 v132, v133
	v_max_f32_e32 v132, v132, v133
	v_cmp_lt_f32_e32 vcc, s4, v132
	s_cbranch_vccnz .Lat_rareg2b

.Lat_backg4a:
	v_exp_f32_e32 v96, v96
	v_exp_f32_e32 v97, v97
	v_exp_f32_e32 v98, v98
	v_exp_f32_e32 v99, v99
	v_exp_f32_e32 v100, v100
	v_exp_f32_e32 v101, v101
	v_exp_f32_e32 v102, v102
	v_exp_f32_e32 v103, v103
	v_cvt_pk_bf16_f32 v162, v96, v97
	v_cvt_pk_bf16_f32 v163, v98, v99
	v_cvt_pk_bf16_f32 v164, v100, v101
	v_cvt_pk_bf16_f32 v165, v102, v103
	v_pk_add_f32 v[128:129], v[128:129], v[96:97]
	v_pk_add_f32 v[128:129], v[128:129], v[98:99]
	v_pk_add_f32 v[128:129], v[128:129], v[100:101]
	v_pk_add_f32 v[128:129], v[128:129], v[102:103]
	s_waitcnt lgkmcnt(12)
	v_mfma_f32_32x32x16_bf16 v[0:15], v[162:165], v[168:171], v[0:15]
	v_exp_f32_e32 v104, v104
	v_exp_f32_e32 v105, v105
	v_exp_f32_e32 v106, v106
	v_exp_f32_e32 v107, v107
	v_mfma_f32_32x32x16_bf16 v[16:31], v[162:165], v[172:175], v[16:31]
	v_exp_f32_e32 v108, v108
	v_exp_f32_e32 v109, v109
	v_exp_f32_e32 v110, v110
	v_exp_f32_e32 v111, v111
	v_cvt_pk_bf16_f32 v162, v104, v105
	v_cvt_pk_bf16_f32 v163, v106, v107
	v_cvt_pk_bf16_f32 v164, v108, v109
	v_cvt_pk_bf16_f32 v165, v110, v111
	v_pk_add_f32 v[128:129], v[128:129], v[104:105]
	v_pk_add_f32 v[128:129], v[128:129], v[106:107]
	v_pk_add_f32 v[128:129], v[128:129], v[108:109]
	v_pk_add_f32 v[128:129], v[128:129], v[110:111]
	s_waitcnt lgkmcnt(8)
	v_mfma_f32_32x32x16_bf16 v[0:15], v[162:165], v[176:179], v[0:15]
	v_exp_f32_e32 v112, v112
	v_exp_f32_e32 v113, v113
	v_exp_f32_e32 v114, v114
	v_exp_f32_e32 v115, v115
	v_mfma_f32_32x32x16_bf16 v[16:31], v[162:165], v[180:183], v[16:31]
	v_mfma_f32_32x32x16_bf16 v[96:111], v[48:51], v[150:153], v[64:79]
	v_exp_f32_e32 v116, v116
	v_exp_f32_e32 v117, v117
	v_exp_f32_e32 v118, v118
	v_exp_f32_e32 v119, v119
	v_mfma_f32_32x32x16_bf16 v[96:111], v[52:55], v[154:157], v[96:111]
	v_cvt_pk_bf16_f32 v162, v112, v113
	v_cvt_pk_bf16_f32 v163, v114, v115
	v_cvt_pk_bf16_f32 v164, v116, v117
	v_cvt_pk_bf16_f32 v165, v118, v119
	v_pk_add_f32 v[128:129], v[128:129], v[112:113]
	v_pk_add_f32 v[128:129], v[128:129], v[114:115]
	v_pk_add_f32 v[128:129], v[128:129], v[116:117]
	v_pk_add_f32 v[128:129], v[128:129], v[118:119]
	s_waitcnt lgkmcnt(4)
	v_mfma_f32_32x32x16_bf16 v[0:15], v[162:165], v[184:187], v[0:15]
	v_exp_f32_e32 v120, v120
	v_exp_f32_e32 v121, v121
	v_exp_f32_e32 v122, v122
	v_exp_f32_e32 v123, v123
	v_mfma_f32_32x32x16_bf16 v[16:31], v[162:165], v[188:191], v[16:31]
	v_exp_f32_e32 v124, v124
	v_exp_f32_e32 v125, v125
	v_exp_f32_e32 v126, v126
	v_exp_f32_e32 v127, v127
	v_cvt_pk_bf16_f32 v162, v120, v121
	v_cvt_pk_bf16_f32 v163, v122, v123
	v_cvt_pk_bf16_f32 v164, v124, v125
	v_cvt_pk_bf16_f32 v165, v126, v127
	v_pk_add_f32 v[128:129], v[128:129], v[120:121]
	v_pk_add_f32 v[128:129], v[128:129], v[122:123]
	v_pk_add_f32 v[128:129], v[128:129], v[124:125]
	v_pk_add_f32 v[128:129], v[128:129], v[126:127]
	v_mfma_f32_32x32x16_bf16 v[112:127], v[56:59], v[150:153], v[64:79]
	v_mfma_f32_32x32x16_bf16 v[112:127], v[60:63], v[154:157], v[112:127]
	s_waitcnt lgkmcnt(0)
	v_mfma_f32_32x32x16_bf16 v[0:15], v[162:165], v[192:195], v[0:15]
	v_max3_f32 v132, v96, v97, v98
	v_max3_f32 v133, v99, v100, v101
	v_max3_f32 v132, v132, v102, v103
	v_max3_f32 v133, v133, v104, v105
	v_max3_f32 v132, v132, v106, v107
	v_max3_f32 v133, v133, v108, v109
	v_max3_f32 v132, v132, v110, v111
	v_mfma_f32_32x32x16_bf16 v[16:31], v[162:165], v[196:199], v[16:31]
	ds_read_b128 v[48:51], v144 offset:40960
	ds_read_b128 v[52:55], v145 offset:40960
	ds_read_b128 v[56:59], v144 offset:45056
	ds_read_b128 v[60:63], v145 offset:45056
	v_max3_f32 v133, v133, v112, v113
	v_max3_f32 v132, v132, v114, v115
	v_max3_f32 v133, v133, v116, v117
	v_max3_f32 v132, v132, v118, v119
	v_max3_f32 v133, v133, v120, v121
	v_max3_f32 v132, v132, v122, v123
	v_max3_f32 v133, v133, v124, v125
	v_max3_f32 v132, v132, v126, v127
	v_max_f32_e32 v132, v132, v133
	v_mov_b32_e32 v133, v132
	s_nop 1
	v_permlane32_swap_b32_e32 v132, v133
	v_max_f32_e32 v132, v132, v133
	v_cmp_lt_f32_e32 vcc, s4, v132
	s_cbranch_vccnz .Lat_rareg4b
